# v20 = v12 + waves 0-3 skip the causal unit's final step and drain (their last two KV tiles are fully masked: exact zeros)
# speedup vs baseline: 1.0039x; 1.0039x over previous
.LBB0_656:
	v_readlane_b32 s46, v246, 38
	v_readlane_b32 s101, v246, 60
	s_nop 0
	s_cmp_lt_u32 s101, 4
	s_cbranch_scc0 .Lfs_go
	s_waitcnt lgkmcnt(0)
	v_mov_b32_e32 v64, v166
	v_mov_b32_e32 v32, v166
	s_nop 1
	v_permlane32_swap_b32_e32 v64, v32
	s_mov_b64 s[0:1], exec
	v_readlane_b32 s8, v245, 61
	v_readlane_b32 s9, v245, 62
	s_and_b64 s[8:9], s[0:1], s[8:9]
	s_mov_b64 exec, s[8:9]
	s_cbranch_execz .LBB0_546
	v_add_f32_e32 v32, v64, v32
	ds_write_b32 v172, v32 offset:128
	s_branch .LBB0_546
.Lfs_go:
	v_add_u32_e32 v120, s82, v179
	ds_read_b128 v[220:223], v120 offset:2560
	v_add_u32_e32 v167, s84, v180
	v_add_f32_e32 v64, v48, v49
	v_add_f32_e32 v64, v50, v64
	v_add_f32_e32 v64, v51, v64
	v_add_f32_e32 v64, v52, v64
	v_cvt_pk_bf16_f32 v132, v48, v49
	s_waitcnt lgkmcnt(3)
	v_mfma_f32_32x32x16_bf16 v[80:95], v[80:83], v[116:119], 0
	ds_read_b128 v[224:227], v120 offset:4096
	v_add_f32_e32 v48, v53, v64
	v_add_f32_e32 v48, v54, v48
	v_add_f32_e32 v121, v55, v48
	v_cvt_pk_bf16_f32 v133, v50, v51
	s_waitcnt lgkmcnt(3)
	v_mfma_f32_32x32x16_bf16 v[64:79], v[136:139], v[116:119], 0
	ds_read_b128 v[48:51], v120 offset:4608
	v_add_f32_e32 v116, v56, v121
	v_add_f32_e32 v116, v57, v116
	v_add_f32_e32 v121, v58, v116
	v_cvt_pk_bf16_f32 v134, v52, v53
	s_waitcnt lgkmcnt(3)
	v_mfma_f32_32x32x16_bf16 v[80:95], v[140:143], v[112:115], v[80:95]
	ds_read_b128 v[116:119], v120 offset:6144
	v_add_f32_e32 v52, v59, v121
	v_add_f32_e32 v52, v60, v52
	s_waitcnt lgkmcnt(3)
	v_mfma_f32_32x32x16_bf16 v[64:79], v[220:223], v[112:115], v[64:79]
	v_add_f32_e32 v112, v61, v52
	v_cvt_pk_bf16_f32 v135, v54, v55
	ds_read_b128 v[52:55], v120 offset:6656
	v_add_f32_e32 v112, v62, v112
	v_add_f32_e32 v112, v63, v112
	v_add_f32_e32 v121, v32, v112
	v_cvt_pk_bf16_f32 v128, v56, v57
	s_waitcnt lgkmcnt(3)
	v_mfma_f32_32x32x16_bf16 v[80:95], v[224:227], v[104:107], v[80:95]
	ds_read_b128 v[112:115], v120 offset:8192
	s_waitcnt lgkmcnt(3)
	v_mfma_f32_32x32x16_bf16 v[64:79], v[48:51], v[104:107], v[64:79]
	v_add_f32_e32 v48, v33, v121
	v_add_f32_e32 v48, v34, v48
	v_add_f32_e32 v56, v35, v48
	v_cvt_pk_bf16_f32 v129, v58, v59
	ds_read_b128 v[48:51], v120 offset:8704
	v_add_f32_e32 v56, v36, v56
	v_add_f32_e32 v56, v37, v56
	v_add_f32_e32 v104, v38, v56
	v_cvt_pk_bf16_f32 v130, v60, v61
	s_waitcnt lgkmcnt(3)
	v_mfma_f32_32x32x16_bf16 v[80:95], v[116:119], v[96:99], v[80:95]
	ds_read_b128 v[56:59], v120 offset:10240
	s_waitcnt lgkmcnt(3)
	v_mfma_f32_32x32x16_bf16 v[64:79], v[52:55], v[96:99], v[64:79]
	v_add_f32_e32 v52, v39, v104
	v_add_f32_e32 v52, v40, v52
	v_add_f32_e32 v60, v41, v52
	v_cvt_pk_bf16_f32 v131, v62, v63
	ds_read_b128 v[52:55], v120 offset:10752
	v_add_f32_e32 v60, v42, v60
	v_add_f32_e32 v60, v43, v60
	v_cvt_pk_bf16_f32 v124, v32, v33
	v_cvt_pk_bf16_f32 v125, v34, v35
	s_waitcnt lgkmcnt(3)
	v_mfma_f32_32x32x16_bf16 v[80:95], v[112:115], v[108:111], v[80:95]
	ds_read_b64_tr_b16 v[96:97], v167 offset:49152
	ds_read_b64_tr_b16 v[98:99], v167 offset:49664
	v_add_f32_e32 v32, v44, v60
	v_add_f32_e32 v32, v45, v32
	v_cvt_pk_bf16_f32 v126, v36, v37
	v_cvt_pk_bf16_f32 v127, v38, v39
	s_waitcnt lgkmcnt(4)
	v_mfma_f32_32x32x16_bf16 v[64:79], v[48:51], v[108:111], v[64:79]
	ds_read_b64_tr_b16 v[108:109], v167 offset:53248
	ds_read_b64_tr_b16 v[110:111], v167 offset:53760
	v_add_f32_e32 v32, v46, v32
	v_cvt_pk_bf16_f32 v120, v40, v41
	v_cvt_pk_bf16_f32 v121, v42, v43
	s_waitcnt lgkmcnt(5)
	v_mfma_f32_32x32x16_bf16 v[80:95], v[56:59], v[100:103], v[80:95]
	ds_read_b64_tr_b16 v[104:105], v167 offset:50176
	ds_read_b64_tr_b16 v[106:107], v167 offset:50688
	v_add_f32_e32 v32, v47, v32
	v_cvt_pk_bf16_f32 v122, v44, v45
	v_cvt_pk_bf16_f32 v123, v46, v47
	s_waitcnt lgkmcnt(6)
	v_mfma_f32_32x32x16_bf16 v[64:79], v[52:55], v[100:103], v[64:79]
	v_readlane_b32 s0, v244, 1
	v_readlane_b32 s1, v244, 2
	v_add_f32_e32 v100, v166, v32
	s_nop 1
	v_cndmask_b32_e64 v49, v218, v81, s[74:75]
	v_cndmask_b32_e64 v33, v80, v218, s[0:1]
	v_readlane_b32 s0, v244, 3
	v_readlane_b32 s1, v244, 4
	v_cndmask_b32_e64 v48, v33, v80, s[74:75]
	v_cndmask_b32_e64 v53, v85, v218, s[90:91]
	s_nop 0
	v_cndmask_b32_e64 v32, v64, v218, s[0:1]
	v_readlane_b32 s0, v244, 5
	v_readlane_b32 s1, v244, 6
	v_cndmask_b32_e64 v37, v69, v218, s[50:51]
	v_cndmask_b32_e64 v54, v86, v218, s[94:95]
	v_cndmask_b32_e64 v33, v65, v218, s[0:1]
	v_readlane_b32 s0, v244, 7
	v_readlane_b32 s1, v244, 8
	v_cndmask_b32_e64 v38, v70, v218, s[96:97]
	v_cndmask_b32_e64 v55, v87, v218, s[4:5]
	v_cndmask_b32_e64 v50, v82, v218, s[0:1]
	v_readlane_b32 s0, v244, 9
	v_readlane_b32 s1, v244, 10
	v_cndmask_b32_e64 v39, v71, v218, s[6:7]
	v_cndmask_b32_e64 v56, v88, v218, s[10:11]
	v_cndmask_b32_e64 v34, v66, v218, s[0:1]
	v_readlane_b32 s0, v244, 11
	v_readlane_b32 s1, v244, 12
	v_cndmask_b32_e64 v40, v72, v218, s[12:13]
	v_cndmask_b32_e64 v57, v89, v218, s[14:15]
	v_cndmask_b32_e64 v51, v83, v218, s[0:1]
	v_readlane_b32 s0, v244, 13
	v_readlane_b32 s1, v244, 14
	v_cndmask_b32_e64 v41, v73, v218, s[16:17]
	v_cndmask_b32_e64 v58, v90, v218, s[18:19]
	v_cndmask_b32_e64 v35, v67, v218, s[0:1]
	v_readlane_b32 s0, v244, 15
	v_readlane_b32 s1, v244, 16
	v_cndmask_b32_e64 v42, v74, v218, s[20:21]
	v_cndmask_b32_e64 v59, v91, v218, s[22:23]
	v_cndmask_b32_e64 v52, v84, v218, s[0:1]
	v_readlane_b32 s0, v244, 17
	v_readlane_b32 s1, v244, 18
	v_cndmask_b32_e64 v43, v75, v218, s[24:25]
	v_cndmask_b32_e64 v60, v92, v218, s[26:27]
	v_cndmask_b32_e64 v36, v68, v218, s[0:1]
	v_cndmask_b32_e64 v44, v76, v218, s[28:29]
	v_cndmask_b32_e64 v61, v93, v218, s[30:31]
	v_cndmask_b32_e64 v45, v77, v218, s[34:35]
	v_cndmask_b32_e64 v62, v94, v218, s[36:37]
	v_cndmask_b32_e64 v46, v78, v218, s[38:39]
	v_cndmask_b32_e64 v63, v95, v218, s[40:41]
	s_and_b64 vcc, exec, s[44:45]
	v_cndmask_b32_e64 v47, v79, v218, s[42:43]
	s_cbranch_vccnz .LBB0_660
	v_max_f32_e32 v64, v49, v49
	v_max_f32_e32 v65, v48, v48
	v_max_f32_e32 v64, v65, v64
	v_max3_f32 v65, v50, v51, v33
	v_max3_f32 v64, v64, v32, v34
	v_max3_f32 v64, v64, v35, v52
	v_max3_f32 v65, v65, v54, v55
	v_max3_f32 v64, v64, v53, v36
	v_max3_f32 v65, v65, v38, v39
	v_max3_f32 v64, v64, v37, v56
	v_max3_f32 v65, v65, v58, v59
	v_max3_f32 v64, v64, v57, v40
	v_max3_f32 v65, v65, v42, v43
	v_max3_f32 v64, v64, v41, v60
	v_max3_f32 v65, v65, v62, v63
	v_max3_f32 v64, v64, v61, v44
	v_max3_f32 v65, v65, v46, v47
	v_max3_f32 v64, v64, v45, v65
	v_sub_f32_e32 v65, v64, v145
	v_cmp_lt_f32_e32 vcc, s77, v65
	s_cmp_lg_u64 vcc, 0
	s_cselect_b64 s[60:61], -1, 0
	s_cbranch_vccnz .LBB0_665
	s_andn2_b64 vcc, exec, s[62:63]
	s_cbranch_vccnz .LBB0_660
